# HGRN2: partial-output reduction and row stores moved to idle waves 4-7
# baseline (speedup 1.0000x reference)
.LBB0_816:
	v_cndmask_b32_e64 v48, 0, 1, s[6:7]
	v_cmp_ne_u32_e64 s[0:1], 1, v48
	s_andn2_b64 vcc, exec, s[6:7]
	s_and_b32 s40, s23, 1
	s_cbranch_vccnz .LBB0_820
.LBB0_819:
	v_add_u32_e32 v48, 0, v46
	v_add_u32_e32 v50, 0, v45
	v_add_u32_e32 v49, 0x1c000, v48
	v_add_u32_e32 v51, 0x1a200, v50
	v_add_u32_e32 v52, 0x1c200, v50
	v_add_u32_e32 v50, 0, v44
	v_add_u32_e32 v48, 0x1a000, v48
	v_add_u32_e32 v53, 0x12000, v50
	v_add_u32_e32 v54, 0x12080, v50
	v_add_u32_e32 v55, 0x12100, v50
	v_add_u32_e32 v56, 0x12180, v50
	ds_read_u16 v49, v49
	ds_read_u16 v51, v51
	ds_read_u16 v52, v52
	ds_read_u16 v116, v53
	ds_read_u16 v117, v54
	ds_read_u16 v118, v55
	ds_read_u16 v119, v56
	ds_read_u16 v48, v48
	s_waitcnt lgkmcnt(7)
	v_lshlrev_b32_e32 v49, 16, v49
	v_mul_f32_e64 v53, |v49|, s83
	v_exp_f32_e32 v53, v53
	v_cmp_le_f32_e32 vcc, 0, v49
	s_waitcnt lgkmcnt(0)
	v_lshlrev_b32_e32 v48, 16, v48
	v_lshlrev_b32_e32 v52, 16, v52
	v_add_f32_e32 v54, 1.0, v53
	v_rcp_f32_e32 v54, v54
	v_mul_f32_e64 v55, |v52|, s83
	v_exp_f32_e32 v55, v55
	v_lshlrev_b32_e32 v51, 16, v51
	v_mul_f32_e32 v53, v53, v54
	v_cndmask_b32_e32 v49, v53, v54, vcc
	v_mul_f32_e32 v54, 0xbfb8aa3b, v48
	v_exp_f32_e32 v54, v54
	v_mul_f32_e32 v57, 0xbfb8aa3b, v51
	v_exp_f32_e32 v57, v57
	v_add_f32_e32 v56, 1.0, v55
	v_add_f32_e32 v54, 1.0, v54
	v_rcp_f32_e32 v54, v54
	v_fma_f32 v49, v31, v49, v23
	v_add_u32_e32 v53, v30, v33
	v_rcp_f32_e32 v56, v56
	v_mul_f32_e32 v48, v54, v48
	ds_write2_b32 v53, v49, v48 offset1:4
	v_add_f32_e32 v49, 1.0, v57
	v_rcp_f32_e32 v49, v49
	v_mul_f32_e32 v48, v55, v56
	v_cmp_le_f32_e32 vcc, 0, v52
	v_add_u32_e32 v52, 0x12380, v50
	v_mul_f32_e32 v49, v49, v51
	v_cndmask_b32_e32 v48, v48, v56, vcc
	v_fma_f32 v48, v31, v48, v23
	ds_write2_b32 v37, v48, v49 offset1:4
	v_mov_b32_e32 v124, s18
	v_add_u32_e32 v125, 0x12000, v50
	v_lshl_add_u32 v51, s40, 15, v34
	ds_read_b128 v[52:55], v124 offset:0
	ds_read_b128 v[56:59], v124 offset:16
	ds_read_b128 v[60:63], v124 offset:32
	ds_read_b128 v[64:67], v124 offset:48
	ds_read_b128 v[68:71], v124 offset:64
	ds_read_b128 v[72:75], v124 offset:80
	ds_read_b128 v[76:79], v124 offset:96
	ds_read_b128 v[80:83], v124 offset:112
	s_waitcnt lgkmcnt(0)
	v_lshlrev_b32_e32 v126, 16, v116
	v_pk_add_f32 v[130:131], v[26:27], v[126:127] op_sel_hi:[1,0] neg_lo:[0,1] neg_hi:[0,1]
	v_pk_add_f32 v[132:133], v[24:25], v[126:127] op_sel_hi:[1,0] neg_lo:[0,1] neg_hi:[0,1]
	v_lshlrev_b32_e32 v128, 16, v117
	v_pk_fma_f32 v[26:27], v[130:131], v[52:53], v[126:127] op_sel_hi:[1,1,0]
	v_pk_fma_f32 v[24:25], v[132:133], v[54:55], v[126:127] op_sel_hi:[1,1,0]
	ds_read_u16 v120, v125 offset:512
	ds_read_u16 v121, v125 offset:640
	ds_read_u16 v122, v125 offset:768
	ds_read_u16 v123, v125 offset:896
	ds_read_b128 v[84:87], v124 offset:128
	ds_read_b128 v[88:91], v124 offset:144
	ds_read_b128 v[92:95], v124 offset:160
	ds_read_b128 v[96:99], v124 offset:176
	ds_read_b128 v[100:103], v124 offset:192
	ds_read_b128 v[104:107], v124 offset:208
	ds_read_b128 v[108:111], v124 offset:224
	ds_read_b128 v[112:115], v124 offset:240
	v_pk_mul_f32 v[134:135], v[58:59], v[24:25]
	v_pk_add_f32 v[130:131], v[26:27], v[128:129] op_sel_hi:[1,0] neg_lo:[0,1] neg_hi:[0,1]
	v_pk_add_f32 v[132:133], v[24:25], v[128:129] op_sel_hi:[1,0] neg_lo:[0,1] neg_hi:[0,1]
	v_lshlrev_b32_e32 v126, 16, v118
	v_pk_fma_f32 v[134:135], v[56:57], v[26:27], v[134:135]
	v_pk_fma_f32 v[26:27], v[130:131], v[60:61], v[128:129] op_sel_hi:[1,1,0]
	v_pk_fma_f32 v[24:25], v[132:133], v[62:63], v[128:129] op_sel_hi:[1,1,0]
	v_add_f32_e32 v136, v134, v135
	v_pk_mul_f32 v[134:135], v[66:67], v[24:25]
	v_pk_add_f32 v[130:131], v[26:27], v[126:127] op_sel_hi:[1,0] neg_lo:[0,1] neg_hi:[0,1]
	v_pk_add_f32 v[132:133], v[24:25], v[126:127] op_sel_hi:[1,0] neg_lo:[0,1] neg_hi:[0,1]
	v_lshlrev_b32_e32 v128, 16, v119
	v_pk_fma_f32 v[134:135], v[64:65], v[26:27], v[134:135]
	v_pk_fma_f32 v[26:27], v[130:131], v[68:69], v[126:127] op_sel_hi:[1,1,0]
	v_pk_fma_f32 v[24:25], v[132:133], v[70:71], v[126:127] op_sel_hi:[1,1,0]
	v_add_f32_e32 v137, v134, v135
	ds_write2st64_b32 v51, v136, v137 offset0:32 offset1:33
	v_pk_mul_f32 v[134:135], v[74:75], v[24:25]
	v_pk_add_f32 v[130:131], v[26:27], v[128:129] op_sel_hi:[1,0] neg_lo:[0,1] neg_hi:[0,1]
	v_pk_add_f32 v[132:133], v[24:25], v[128:129] op_sel_hi:[1,0] neg_lo:[0,1] neg_hi:[0,1]
	v_pk_fma_f32 v[134:135], v[72:73], v[26:27], v[134:135]
	v_pk_fma_f32 v[26:27], v[130:131], v[76:77], v[128:129] op_sel_hi:[1,1,0]
	v_pk_fma_f32 v[24:25], v[132:133], v[78:79], v[128:129] op_sel_hi:[1,1,0]
	v_add_f32_e32 v138, v134, v135
	s_waitcnt lgkmcnt(1)
	v_lshlrev_b32_e32 v126, 16, v120
	v_pk_mul_f32 v[134:135], v[82:83], v[24:25]
	v_pk_add_f32 v[130:131], v[26:27], v[126:127] op_sel_hi:[1,0] neg_lo:[0,1] neg_hi:[0,1]
	v_pk_add_f32 v[132:133], v[24:25], v[126:127] op_sel_hi:[1,0] neg_lo:[0,1] neg_hi:[0,1]
	v_lshlrev_b32_e32 v128, 16, v121
	v_pk_fma_f32 v[134:135], v[80:81], v[26:27], v[134:135]
	v_pk_fma_f32 v[26:27], v[130:131], v[84:85], v[126:127] op_sel_hi:[1,1,0]
	v_pk_fma_f32 v[24:25], v[132:133], v[86:87], v[126:127] op_sel_hi:[1,1,0]
	v_add_f32_e32 v139, v134, v135
	ds_write2st64_b32 v51, v138, v139 offset0:34 offset1:35
	ds_read_u16 v116, v125 offset:1024
	ds_read_u16 v117, v125 offset:1152
	ds_read_u16 v118, v125 offset:1280
	ds_read_u16 v119, v125 offset:1408
	ds_read_b128 v[52:55], v124 offset:256
	ds_read_b128 v[56:59], v124 offset:272
	ds_read_b128 v[60:63], v124 offset:288
	ds_read_b128 v[64:67], v124 offset:304
	ds_read_b128 v[68:71], v124 offset:320
	ds_read_b128 v[72:75], v124 offset:336
	ds_read_b128 v[76:79], v124 offset:352
	ds_read_b128 v[80:83], v124 offset:368
	v_pk_mul_f32 v[134:135], v[90:91], v[24:25]
	v_pk_add_f32 v[130:131], v[26:27], v[128:129] op_sel_hi:[1,0] neg_lo:[0,1] neg_hi:[0,1]
	v_pk_add_f32 v[132:133], v[24:25], v[128:129] op_sel_hi:[1,0] neg_lo:[0,1] neg_hi:[0,1]
	v_lshlrev_b32_e32 v126, 16, v122
	v_pk_fma_f32 v[134:135], v[88:89], v[26:27], v[134:135]
	v_pk_fma_f32 v[26:27], v[130:131], v[92:93], v[128:129] op_sel_hi:[1,1,0]
	v_pk_fma_f32 v[24:25], v[132:133], v[94:95], v[128:129] op_sel_hi:[1,1,0]
	v_add_f32_e32 v136, v134, v135
	v_pk_mul_f32 v[134:135], v[98:99], v[24:25]
	v_pk_add_f32 v[130:131], v[26:27], v[126:127] op_sel_hi:[1,0] neg_lo:[0,1] neg_hi:[0,1]
	v_pk_add_f32 v[132:133], v[24:25], v[126:127] op_sel_hi:[1,0] neg_lo:[0,1] neg_hi:[0,1]
	v_lshlrev_b32_e32 v128, 16, v123
	v_pk_fma_f32 v[134:135], v[96:97], v[26:27], v[134:135]
	v_pk_fma_f32 v[26:27], v[130:131], v[100:101], v[126:127] op_sel_hi:[1,1,0]
	v_pk_fma_f32 v[24:25], v[132:133], v[102:103], v[126:127] op_sel_hi:[1,1,0]
	v_add_f32_e32 v137, v134, v135
	ds_write2st64_b32 v51, v136, v137 offset0:36 offset1:37
	v_pk_mul_f32 v[134:135], v[106:107], v[24:25]
	v_pk_add_f32 v[130:131], v[26:27], v[128:129] op_sel_hi:[1,0] neg_lo:[0,1] neg_hi:[0,1]
	v_pk_add_f32 v[132:133], v[24:25], v[128:129] op_sel_hi:[1,0] neg_lo:[0,1] neg_hi:[0,1]
	v_pk_fma_f32 v[134:135], v[104:105], v[26:27], v[134:135]
	v_pk_fma_f32 v[26:27], v[130:131], v[108:109], v[128:129] op_sel_hi:[1,1,0]
	v_pk_fma_f32 v[24:25], v[132:133], v[110:111], v[128:129] op_sel_hi:[1,1,0]
	v_add_f32_e32 v138, v134, v135
	s_waitcnt lgkmcnt(1)
	v_lshlrev_b32_e32 v126, 16, v116
	v_pk_mul_f32 v[134:135], v[114:115], v[24:25]
	v_pk_add_f32 v[130:131], v[26:27], v[126:127] op_sel_hi:[1,0] neg_lo:[0,1] neg_hi:[0,1]
	v_pk_add_f32 v[132:133], v[24:25], v[126:127] op_sel_hi:[1,0] neg_lo:[0,1] neg_hi:[0,1]
	v_lshlrev_b32_e32 v128, 16, v117
	v_pk_fma_f32 v[134:135], v[112:113], v[26:27], v[134:135]
	v_pk_fma_f32 v[26:27], v[130:131], v[52:53], v[126:127] op_sel_hi:[1,1,0]
	v_pk_fma_f32 v[24:25], v[132:133], v[54:55], v[126:127] op_sel_hi:[1,1,0]
	v_add_f32_e32 v139, v134, v135
	ds_write2st64_b32 v51, v138, v139 offset0:38 offset1:39
	ds_read_u16 v120, v125 offset:1536
	ds_read_u16 v121, v125 offset:1664
	ds_read_u16 v122, v125 offset:1792
	ds_read_u16 v123, v125 offset:1920
	ds_read_b128 v[84:87], v124 offset:384
	ds_read_b128 v[88:91], v124 offset:400
	ds_read_b128 v[92:95], v124 offset:416
	ds_read_b128 v[96:99], v124 offset:432
	ds_read_b128 v[100:103], v124 offset:448
	ds_read_b128 v[104:107], v124 offset:464
	ds_read_b128 v[108:111], v124 offset:480
	ds_read_b128 v[112:115], v124 offset:496
	v_pk_mul_f32 v[134:135], v[58:59], v[24:25]
	v_pk_add_f32 v[130:131], v[26:27], v[128:129] op_sel_hi:[1,0] neg_lo:[0,1] neg_hi:[0,1]
	v_pk_add_f32 v[132:133], v[24:25], v[128:129] op_sel_hi:[1,0] neg_lo:[0,1] neg_hi:[0,1]
	v_lshlrev_b32_e32 v126, 16, v118
	v_pk_fma_f32 v[134:135], v[56:57], v[26:27], v[134:135]
	v_pk_fma_f32 v[26:27], v[130:131], v[60:61], v[128:129] op_sel_hi:[1,1,0]
	v_pk_fma_f32 v[24:25], v[132:133], v[62:63], v[128:129] op_sel_hi:[1,1,0]
	v_add_f32_e32 v136, v134, v135
	v_pk_mul_f32 v[134:135], v[66:67], v[24:25]
	v_pk_add_f32 v[130:131], v[26:27], v[126:127] op_sel_hi:[1,0] neg_lo:[0,1] neg_hi:[0,1]
	v_pk_add_f32 v[132:133], v[24:25], v[126:127] op_sel_hi:[1,0] neg_lo:[0,1] neg_hi:[0,1]
	v_lshlrev_b32_e32 v128, 16, v119
	v_pk_fma_f32 v[134:135], v[64:65], v[26:27], v[134:135]
	v_pk_fma_f32 v[26:27], v[130:131], v[68:69], v[126:127] op_sel_hi:[1,1,0]
	v_pk_fma_f32 v[24:25], v[132:133], v[70:71], v[126:127] op_sel_hi:[1,1,0]
	v_add_f32_e32 v137, v134, v135
	ds_write2st64_b32 v51, v136, v137 offset0:40 offset1:41
	v_pk_mul_f32 v[134:135], v[74:75], v[24:25]
	v_pk_add_f32 v[130:131], v[26:27], v[128:129] op_sel_hi:[1,0] neg_lo:[0,1] neg_hi:[0,1]
	v_pk_add_f32 v[132:133], v[24:25], v[128:129] op_sel_hi:[1,0] neg_lo:[0,1] neg_hi:[0,1]
	v_pk_fma_f32 v[134:135], v[72:73], v[26:27], v[134:135]
	v_pk_fma_f32 v[26:27], v[130:131], v[76:77], v[128:129] op_sel_hi:[1,1,0]
	v_pk_fma_f32 v[24:25], v[132:133], v[78:79], v[128:129] op_sel_hi:[1,1,0]
	v_add_f32_e32 v138, v134, v135
	s_waitcnt lgkmcnt(1)
	v_lshlrev_b32_e32 v126, 16, v120
	v_pk_mul_f32 v[134:135], v[82:83], v[24:25]
	v_pk_add_f32 v[130:131], v[26:27], v[126:127] op_sel_hi:[1,0] neg_lo:[0,1] neg_hi:[0,1]
	v_pk_add_f32 v[132:133], v[24:25], v[126:127] op_sel_hi:[1,0] neg_lo:[0,1] neg_hi:[0,1]
	v_lshlrev_b32_e32 v128, 16, v121
	v_pk_fma_f32 v[134:135], v[80:81], v[26:27], v[134:135]
	v_pk_fma_f32 v[26:27], v[130:131], v[84:85], v[126:127] op_sel_hi:[1,1,0]
	v_pk_fma_f32 v[24:25], v[132:133], v[86:87], v[126:127] op_sel_hi:[1,1,0]
	v_add_f32_e32 v139, v134, v135
	ds_write2st64_b32 v51, v138, v139 offset0:42 offset1:43
	ds_read_u16 v116, v125 offset:2048
	ds_read_u16 v117, v125 offset:2176
	ds_read_u16 v118, v125 offset:2304
	ds_read_u16 v119, v125 offset:2432
	ds_read_b128 v[52:55], v124 offset:512
	ds_read_b128 v[56:59], v124 offset:528
	ds_read_b128 v[60:63], v124 offset:544
	ds_read_b128 v[64:67], v124 offset:560
	ds_read_b128 v[68:71], v124 offset:576
	ds_read_b128 v[72:75], v124 offset:592
	ds_read_b128 v[76:79], v124 offset:608
	ds_read_b128 v[80:83], v124 offset:624
	v_pk_mul_f32 v[134:135], v[90:91], v[24:25]
	v_pk_add_f32 v[130:131], v[26:27], v[128:129] op_sel_hi:[1,0] neg_lo:[0,1] neg_hi:[0,1]
	v_pk_add_f32 v[132:133], v[24:25], v[128:129] op_sel_hi:[1,0] neg_lo:[0,1] neg_hi:[0,1]
	v_lshlrev_b32_e32 v126, 16, v122
	v_pk_fma_f32 v[134:135], v[88:89], v[26:27], v[134:135]
	v_pk_fma_f32 v[26:27], v[130:131], v[92:93], v[128:129] op_sel_hi:[1,1,0]
	v_pk_fma_f32 v[24:25], v[132:133], v[94:95], v[128:129] op_sel_hi:[1,1,0]
	v_add_f32_e32 v136, v134, v135
	v_pk_mul_f32 v[134:135], v[98:99], v[24:25]
	v_pk_add_f32 v[130:131], v[26:27], v[126:127] op_sel_hi:[1,0] neg_lo:[0,1] neg_hi:[0,1]
	v_pk_add_f32 v[132:133], v[24:25], v[126:127] op_sel_hi:[1,0] neg_lo:[0,1] neg_hi:[0,1]
	v_lshlrev_b32_e32 v128, 16, v123
	v_pk_fma_f32 v[134:135], v[96:97], v[26:27], v[134:135]
	v_pk_fma_f32 v[26:27], v[130:131], v[100:101], v[126:127] op_sel_hi:[1,1,0]
	v_pk_fma_f32 v[24:25], v[132:133], v[102:103], v[126:127] op_sel_hi:[1,1,0]
	v_add_f32_e32 v137, v134, v135
	ds_write2st64_b32 v51, v136, v137 offset0:44 offset1:45
	v_pk_mul_f32 v[134:135], v[106:107], v[24:25]
	v_pk_add_f32 v[130:131], v[26:27], v[128:129] op_sel_hi:[1,0] neg_lo:[0,1] neg_hi:[0,1]
	v_pk_add_f32 v[132:133], v[24:25], v[128:129] op_sel_hi:[1,0] neg_lo:[0,1] neg_hi:[0,1]
	v_pk_fma_f32 v[134:135], v[104:105], v[26:27], v[134:135]
	v_pk_fma_f32 v[26:27], v[130:131], v[108:109], v[128:129] op_sel_hi:[1,1,0]
	v_pk_fma_f32 v[24:25], v[132:133], v[110:111], v[128:129] op_sel_hi:[1,1,0]
	v_add_f32_e32 v138, v134, v135
	s_waitcnt lgkmcnt(1)
	v_lshlrev_b32_e32 v126, 16, v116
	v_pk_mul_f32 v[134:135], v[114:115], v[24:25]
	v_pk_add_f32 v[130:131], v[26:27], v[126:127] op_sel_hi:[1,0] neg_lo:[0,1] neg_hi:[0,1]
	v_pk_add_f32 v[132:133], v[24:25], v[126:127] op_sel_hi:[1,0] neg_lo:[0,1] neg_hi:[0,1]
	v_lshlrev_b32_e32 v128, 16, v117
	v_pk_fma_f32 v[134:135], v[112:113], v[26:27], v[134:135]
	v_pk_fma_f32 v[26:27], v[130:131], v[52:53], v[126:127] op_sel_hi:[1,1,0]
	v_pk_fma_f32 v[24:25], v[132:133], v[54:55], v[126:127] op_sel_hi:[1,1,0]
	v_add_f32_e32 v139, v134, v135
	ds_write2st64_b32 v51, v138, v139 offset0:46 offset1:47
	ds_read_u16 v120, v125 offset:2560
	ds_read_u16 v121, v125 offset:2688
	ds_read_u16 v122, v125 offset:2816
	ds_read_u16 v123, v125 offset:2944
	ds_read_b128 v[84:87], v124 offset:640
	ds_read_b128 v[88:91], v124 offset:656
	ds_read_b128 v[92:95], v124 offset:672
	ds_read_b128 v[96:99], v124 offset:688
	ds_read_b128 v[100:103], v124 offset:704
	ds_read_b128 v[104:107], v124 offset:720
	ds_read_b128 v[108:111], v124 offset:736
	ds_read_b128 v[112:115], v124 offset:752
	v_pk_mul_f32 v[134:135], v[58:59], v[24:25]
	v_pk_add_f32 v[130:131], v[26:27], v[128:129] op_sel_hi:[1,0] neg_lo:[0,1] neg_hi:[0,1]
	v_pk_add_f32 v[132:133], v[24:25], v[128:129] op_sel_hi:[1,0] neg_lo:[0,1] neg_hi:[0,1]
	v_lshlrev_b32_e32 v126, 16, v118
	v_pk_fma_f32 v[134:135], v[56:57], v[26:27], v[134:135]
	v_pk_fma_f32 v[26:27], v[130:131], v[60:61], v[128:129] op_sel_hi:[1,1,0]
	v_pk_fma_f32 v[24:25], v[132:133], v[62:63], v[128:129] op_sel_hi:[1,1,0]
	v_add_f32_e32 v136, v134, v135
	v_pk_mul_f32 v[134:135], v[66:67], v[24:25]
	v_pk_add_f32 v[130:131], v[26:27], v[126:127] op_sel_hi:[1,0] neg_lo:[0,1] neg_hi:[0,1]
	v_pk_add_f32 v[132:133], v[24:25], v[126:127] op_sel_hi:[1,0] neg_lo:[0,1] neg_hi:[0,1]
	v_lshlrev_b32_e32 v128, 16, v119
	v_pk_fma_f32 v[134:135], v[64:65], v[26:27], v[134:135]
	v_pk_fma_f32 v[26:27], v[130:131], v[68:69], v[126:127] op_sel_hi:[1,1,0]
	v_pk_fma_f32 v[24:25], v[132:133], v[70:71], v[126:127] op_sel_hi:[1,1,0]
	v_add_f32_e32 v137, v134, v135
	ds_write2st64_b32 v51, v136, v137 offset0:48 offset1:49
	v_pk_mul_f32 v[134:135], v[74:75], v[24:25]
	v_pk_add_f32 v[130:131], v[26:27], v[128:129] op_sel_hi:[1,0] neg_lo:[0,1] neg_hi:[0,1]
	v_pk_add_f32 v[132:133], v[24:25], v[128:129] op_sel_hi:[1,0] neg_lo:[0,1] neg_hi:[0,1]
	v_pk_fma_f32 v[134:135], v[72:73], v[26:27], v[134:135]
	v_pk_fma_f32 v[26:27], v[130:131], v[76:77], v[128:129] op_sel_hi:[1,1,0]
	v_pk_fma_f32 v[24:25], v[132:133], v[78:79], v[128:129] op_sel_hi:[1,1,0]
	v_add_f32_e32 v138, v134, v135
	s_waitcnt lgkmcnt(1)
	v_lshlrev_b32_e32 v126, 16, v120
	v_pk_mul_f32 v[134:135], v[82:83], v[24:25]
	v_pk_add_f32 v[130:131], v[26:27], v[126:127] op_sel_hi:[1,0] neg_lo:[0,1] neg_hi:[0,1]
	v_pk_add_f32 v[132:133], v[24:25], v[126:127] op_sel_hi:[1,0] neg_lo:[0,1] neg_hi:[0,1]
	v_lshlrev_b32_e32 v128, 16, v121
	v_pk_fma_f32 v[134:135], v[80:81], v[26:27], v[134:135]
	v_pk_fma_f32 v[26:27], v[130:131], v[84:85], v[126:127] op_sel_hi:[1,1,0]
	v_pk_fma_f32 v[24:25], v[132:133], v[86:87], v[126:127] op_sel_hi:[1,1,0]
	v_add_f32_e32 v139, v134, v135
	ds_write2st64_b32 v51, v138, v139 offset0:50 offset1:51
	ds_read_u16 v116, v125 offset:3072
	ds_read_u16 v117, v125 offset:3200
	ds_read_u16 v118, v125 offset:3328
	ds_read_u16 v119, v125 offset:3456
	ds_read_b128 v[52:55], v124 offset:768
	ds_read_b128 v[56:59], v124 offset:784
	ds_read_b128 v[60:63], v124 offset:800
	ds_read_b128 v[64:67], v124 offset:816
	ds_read_b128 v[68:71], v124 offset:832
	ds_read_b128 v[72:75], v124 offset:848
	ds_read_b128 v[76:79], v124 offset:864
	ds_read_b128 v[80:83], v124 offset:880
	v_pk_mul_f32 v[134:135], v[90:91], v[24:25]
	v_pk_add_f32 v[130:131], v[26:27], v[128:129] op_sel_hi:[1,0] neg_lo:[0,1] neg_hi:[0,1]
	v_pk_add_f32 v[132:133], v[24:25], v[128:129] op_sel_hi:[1,0] neg_lo:[0,1] neg_hi:[0,1]
	v_lshlrev_b32_e32 v126, 16, v122
	v_pk_fma_f32 v[134:135], v[88:89], v[26:27], v[134:135]
	v_pk_fma_f32 v[26:27], v[130:131], v[92:93], v[128:129] op_sel_hi:[1,1,0]
	v_pk_fma_f32 v[24:25], v[132:133], v[94:95], v[128:129] op_sel_hi:[1,1,0]
	v_add_f32_e32 v136, v134, v135
	v_pk_mul_f32 v[134:135], v[98:99], v[24:25]
	v_pk_add_f32 v[130:131], v[26:27], v[126:127] op_sel_hi:[1,0] neg_lo:[0,1] neg_hi:[0,1]
	v_pk_add_f32 v[132:133], v[24:25], v[126:127] op_sel_hi:[1,0] neg_lo:[0,1] neg_hi:[0,1]
	v_lshlrev_b32_e32 v128, 16, v123
	v_pk_fma_f32 v[134:135], v[96:97], v[26:27], v[134:135]
	v_pk_fma_f32 v[26:27], v[130:131], v[100:101], v[126:127] op_sel_hi:[1,1,0]
	v_pk_fma_f32 v[24:25], v[132:133], v[102:103], v[126:127] op_sel_hi:[1,1,0]
	v_add_f32_e32 v137, v134, v135
	ds_write2st64_b32 v51, v136, v137 offset0:52 offset1:53
	v_pk_mul_f32 v[134:135], v[106:107], v[24:25]
	v_pk_add_f32 v[130:131], v[26:27], v[128:129] op_sel_hi:[1,0] neg_lo:[0,1] neg_hi:[0,1]
	v_pk_add_f32 v[132:133], v[24:25], v[128:129] op_sel_hi:[1,0] neg_lo:[0,1] neg_hi:[0,1]
	v_pk_fma_f32 v[134:135], v[104:105], v[26:27], v[134:135]
	v_pk_fma_f32 v[26:27], v[130:131], v[108:109], v[128:129] op_sel_hi:[1,1,0]
	v_pk_fma_f32 v[24:25], v[132:133], v[110:111], v[128:129] op_sel_hi:[1,1,0]
	v_add_f32_e32 v138, v134, v135
	s_waitcnt lgkmcnt(1)
	v_lshlrev_b32_e32 v126, 16, v116
	v_pk_mul_f32 v[134:135], v[114:115], v[24:25]
	v_pk_add_f32 v[130:131], v[26:27], v[126:127] op_sel_hi:[1,0] neg_lo:[0,1] neg_hi:[0,1]
	v_pk_add_f32 v[132:133], v[24:25], v[126:127] op_sel_hi:[1,0] neg_lo:[0,1] neg_hi:[0,1]
	v_lshlrev_b32_e32 v128, 16, v117
	v_pk_fma_f32 v[134:135], v[112:113], v[26:27], v[134:135]
	v_pk_fma_f32 v[26:27], v[130:131], v[52:53], v[126:127] op_sel_hi:[1,1,0]
	v_pk_fma_f32 v[24:25], v[132:133], v[54:55], v[126:127] op_sel_hi:[1,1,0]
	v_add_f32_e32 v139, v134, v135
	ds_write2st64_b32 v51, v138, v139 offset0:54 offset1:55
	ds_read_u16 v120, v125 offset:3584
	ds_read_u16 v121, v125 offset:3712
	ds_read_u16 v122, v125 offset:3840
	ds_read_u16 v123, v125 offset:3968
	ds_read_b128 v[84:87], v124 offset:896
	ds_read_b128 v[88:91], v124 offset:912
	ds_read_b128 v[92:95], v124 offset:928
	ds_read_b128 v[96:99], v124 offset:944
	ds_read_b128 v[100:103], v124 offset:960
	ds_read_b128 v[104:107], v124 offset:976
	ds_read_b128 v[108:111], v124 offset:992
	ds_read_b128 v[112:115], v124 offset:1008
	v_pk_mul_f32 v[134:135], v[58:59], v[24:25]
	v_pk_add_f32 v[130:131], v[26:27], v[128:129] op_sel_hi:[1,0] neg_lo:[0,1] neg_hi:[0,1]
	v_pk_add_f32 v[132:133], v[24:25], v[128:129] op_sel_hi:[1,0] neg_lo:[0,1] neg_hi:[0,1]
	v_lshlrev_b32_e32 v126, 16, v118
	v_pk_fma_f32 v[134:135], v[56:57], v[26:27], v[134:135]
	v_pk_fma_f32 v[26:27], v[130:131], v[60:61], v[128:129] op_sel_hi:[1,1,0]
	v_pk_fma_f32 v[24:25], v[132:133], v[62:63], v[128:129] op_sel_hi:[1,1,0]
	v_add_f32_e32 v136, v134, v135
	v_pk_mul_f32 v[134:135], v[66:67], v[24:25]
	v_pk_add_f32 v[130:131], v[26:27], v[126:127] op_sel_hi:[1,0] neg_lo:[0,1] neg_hi:[0,1]
	v_pk_add_f32 v[132:133], v[24:25], v[126:127] op_sel_hi:[1,0] neg_lo:[0,1] neg_hi:[0,1]
	v_lshlrev_b32_e32 v128, 16, v119
	v_pk_fma_f32 v[134:135], v[64:65], v[26:27], v[134:135]
	v_pk_fma_f32 v[26:27], v[130:131], v[68:69], v[126:127] op_sel_hi:[1,1,0]
	v_pk_fma_f32 v[24:25], v[132:133], v[70:71], v[126:127] op_sel_hi:[1,1,0]
	v_add_f32_e32 v137, v134, v135
	ds_write2st64_b32 v51, v136, v137 offset0:56 offset1:57
	v_pk_mul_f32 v[134:135], v[74:75], v[24:25]
	v_pk_add_f32 v[130:131], v[26:27], v[128:129] op_sel_hi:[1,0] neg_lo:[0,1] neg_hi:[0,1]
	v_pk_add_f32 v[132:133], v[24:25], v[128:129] op_sel_hi:[1,0] neg_lo:[0,1] neg_hi:[0,1]
	v_pk_fma_f32 v[134:135], v[72:73], v[26:27], v[134:135]
	v_pk_fma_f32 v[26:27], v[130:131], v[76:77], v[128:129] op_sel_hi:[1,1,0]
	v_pk_fma_f32 v[24:25], v[132:133], v[78:79], v[128:129] op_sel_hi:[1,1,0]
	v_add_f32_e32 v138, v134, v135
	s_waitcnt lgkmcnt(1)
	v_lshlrev_b32_e32 v126, 16, v120
	v_pk_mul_f32 v[134:135], v[82:83], v[24:25]
	v_pk_add_f32 v[130:131], v[26:27], v[126:127] op_sel_hi:[1,0] neg_lo:[0,1] neg_hi:[0,1]
	v_pk_add_f32 v[132:133], v[24:25], v[126:127] op_sel_hi:[1,0] neg_lo:[0,1] neg_hi:[0,1]
	v_lshlrev_b32_e32 v128, 16, v121
	v_pk_fma_f32 v[134:135], v[80:81], v[26:27], v[134:135]
	v_pk_fma_f32 v[26:27], v[130:131], v[84:85], v[126:127] op_sel_hi:[1,1,0]
	v_pk_fma_f32 v[24:25], v[132:133], v[86:87], v[126:127] op_sel_hi:[1,1,0]
	v_add_f32_e32 v139, v134, v135
	ds_write2st64_b32 v51, v138, v139 offset0:58 offset1:59
	v_pk_mul_f32 v[134:135], v[90:91], v[24:25]
	v_pk_add_f32 v[130:131], v[26:27], v[128:129] op_sel_hi:[1,0] neg_lo:[0,1] neg_hi:[0,1]
	v_pk_add_f32 v[132:133], v[24:25], v[128:129] op_sel_hi:[1,0] neg_lo:[0,1] neg_hi:[0,1]
	v_lshlrev_b32_e32 v126, 16, v122
	v_pk_fma_f32 v[134:135], v[88:89], v[26:27], v[134:135]
	v_pk_fma_f32 v[26:27], v[130:131], v[92:93], v[128:129] op_sel_hi:[1,1,0]
	v_pk_fma_f32 v[24:25], v[132:133], v[94:95], v[128:129] op_sel_hi:[1,1,0]
	v_add_f32_e32 v136, v134, v135
	v_pk_mul_f32 v[134:135], v[98:99], v[24:25]
	v_pk_add_f32 v[130:131], v[26:27], v[126:127] op_sel_hi:[1,0] neg_lo:[0,1] neg_hi:[0,1]
	v_pk_add_f32 v[132:133], v[24:25], v[126:127] op_sel_hi:[1,0] neg_lo:[0,1] neg_hi:[0,1]
	v_lshlrev_b32_e32 v128, 16, v123
	v_pk_fma_f32 v[134:135], v[96:97], v[26:27], v[134:135]
	v_pk_fma_f32 v[26:27], v[130:131], v[100:101], v[126:127] op_sel_hi:[1,1,0]
	v_pk_fma_f32 v[24:25], v[132:133], v[102:103], v[126:127] op_sel_hi:[1,1,0]
	v_add_f32_e32 v137, v134, v135
	ds_write2st64_b32 v51, v136, v137 offset0:60 offset1:61
	v_pk_mul_f32 v[134:135], v[106:107], v[24:25]
	v_pk_add_f32 v[130:131], v[26:27], v[128:129] op_sel_hi:[1,0] neg_lo:[0,1] neg_hi:[0,1]
	v_pk_add_f32 v[132:133], v[24:25], v[128:129] op_sel_hi:[1,0] neg_lo:[0,1] neg_hi:[0,1]
	v_pk_fma_f32 v[134:135], v[104:105], v[26:27], v[134:135]
	v_pk_fma_f32 v[26:27], v[130:131], v[108:109], v[128:129] op_sel_hi:[1,1,0]
	v_pk_fma_f32 v[24:25], v[132:133], v[110:111], v[128:129] op_sel_hi:[1,1,0]
	v_add_f32_e32 v138, v134, v135
	v_pk_mul_f32 v[134:135], v[114:115], v[24:25]
	s_nop 0
	v_pk_fma_f32 v[134:135], v[112:113], v[26:27], v[134:135]
	s_nop 0
	v_add_f32_e32 v139, v134, v135
	ds_write2st64_b32 v51, v138, v139 offset0:62 offset1:63
.LBB0_820:
	s_waitcnt lgkmcnt(0)
	s_barrier
	s_and_b64 vcc, exec, s[0:1]
	s_cbranch_vccz .LBB0_815
	s_lshl_b32 s40, s40, 15
	s_add_i32 s40, s40, s19
	s_addk_i32 s40, 0xe000
	v_add_u32_e32 v28, s40, v32
	ds_read2st64_b32 v[40:41], v28 offset0:32 offset1:33
	ds_read2st64_b32 v[42:43], v28 offset0:64 offset1:65
	ds_read2st64_b32 v[48:49], v28 offset0:96 offset1:97
	ds_read2st64_b32 v[50:51], v28 offset0:128 offset1:129
	ds_read2st64_b32 v[52:53], v28 offset0:130 offset1:131
	s_waitcnt lgkmcnt(4)
	v_add_f32_e32 v38, 0, v40
	s_waitcnt lgkmcnt(3)
	v_add_f32_e32 v38, v38, v42
	s_waitcnt lgkmcnt(2)
	v_add_f32_e32 v38, v38, v48
	s_waitcnt lgkmcnt(1)
	v_add_f32_e32 v38, v38, v50
	v_cvt_pk_bf16_f32 v39, v38, 0
	v_add_f32_e32 v38, 0, v41
	v_add_f32_e32 v38, v38, v43
	ds_read2st64_b32 v[42:43], v28 offset0:34 offset1:35
	v_add_f32_e32 v38, v38, v49
	ds_read2st64_b32 v[48:49], v28 offset0:66 offset1:67
	v_add_f32_e32 v38, v38, v51
	ds_read2st64_b32 v[50:51], v28 offset0:98 offset1:99
	s_waitcnt lgkmcnt(2)
	v_add_f32_e32 v40, 0, v42
	v_cvt_pk_bf16_f32 v38, v38, 0
	s_waitcnt lgkmcnt(1)
	v_add_f32_e32 v40, v40, v48
	ds_read2st64_b32 v[54:55], v28 offset0:132 offset1:133
	s_waitcnt lgkmcnt(1)
	v_add_f32_e32 v40, v40, v50
	v_add_f32_e32 v40, v40, v52
	v_cvt_pk_bf16_f32 v41, v40, 0
	v_add_f32_e32 v40, 0, v43
	v_add_f32_e32 v40, v40, v49
	ds_read2st64_b32 v[48:49], v28 offset0:36 offset1:37
	v_add_f32_e32 v40, v40, v51
	ds_read2st64_b32 v[50:51], v28 offset0:68 offset1:69
	v_add_f32_e32 v40, v40, v53
	ds_read2st64_b32 v[52:53], v28 offset0:100 offset1:101
	s_waitcnt lgkmcnt(2)
	v_add_f32_e32 v42, 0, v48
	v_cvt_pk_bf16_f32 v40, v40, 0
	s_waitcnt lgkmcnt(1)
	v_add_f32_e32 v42, v42, v50
	s_waitcnt lgkmcnt(0)
	v_add_f32_e32 v42, v42, v52
	v_add_f32_e32 v42, v42, v54
	v_cvt_pk_bf16_f32 v43, v42, 0
	v_add_f32_e32 v42, 0, v49
	ds_read2st64_b32 v[48:49], v28 offset0:38 offset1:39
	v_add_f32_e32 v42, v42, v51
	ds_read2st64_b32 v[50:51], v28 offset0:70 offset1:71
	v_add_f32_e32 v42, v42, v53
	ds_read2st64_b32 v[52:53], v28 offset0:102 offset1:103
	v_add_f32_e32 v42, v42, v55
	ds_read2st64_b32 v[54:55], v28 offset0:134 offset1:135
	s_waitcnt lgkmcnt(3)
	v_add_f32_e32 v47, 0, v48
	s_waitcnt lgkmcnt(2)
	v_add_f32_e32 v47, v47, v50
	s_waitcnt lgkmcnt(1)
	v_add_f32_e32 v47, v47, v52
	v_cvt_pk_bf16_f32 v42, v42, 0
	s_waitcnt lgkmcnt(0)
	v_add_f32_e32 v28, v47, v54
	v_cvt_pk_bf16_f32 v47, v28, 0
	v_add_f32_e32 v28, 0, v49
	v_add_f32_e32 v28, v28, v51
	v_add_f32_e32 v28, v28, v53
	v_add_f32_e32 v28, v28, v55
	v_cvt_pk_bf16_f32 v28, v28, 0
	s_add_u32 s41, s12, s16
	s_addc_u32 s48, s13, s17
	s_add_u32 s46, s41, 0xffffffe0
	s_addc_u32 s47, s48, -1
	s_lshl_b64 s[46:47], s[46:47], s39
	v_lshl_add_u64 v[48:49], s[46:47], 1, v[12:13]
	s_add_u32 s46, s41, 0xffffffe1
	s_addc_u32 s47, s48, -1
	s_lshl_b64 s[46:47], s[46:47], s39
	global_store_short v[48:49], v39, off
	v_lshl_add_u64 v[48:49], s[46:47], 1, v[12:13]
	s_add_u32 s46, s41, 0xffffffe2
	s_addc_u32 s47, s48, -1
	s_lshl_b64 s[46:47], s[46:47], s39
	global_store_short v[48:49], v38, off
	v_lshl_add_u64 v[48:49], s[46:47], 1, v[12:13]
	s_add_u32 s46, s41, 0xffffffe3
	s_addc_u32 s47, s48, -1
	s_lshl_b64 s[46:47], s[46:47], s39
	global_store_short v[48:49], v41, off
	v_lshl_add_u64 v[48:49], s[46:47], 1, v[12:13]
	s_add_u32 s46, s41, 0xffffffe4
	s_addc_u32 s47, s48, -1
	s_lshl_b64 s[46:47], s[46:47], s39
	global_store_short v[48:49], v40, off
	v_lshl_add_u64 v[48:49], s[46:47], 1, v[12:13]
	s_add_u32 s46, s41, 0xffffffe5
	s_addc_u32 s47, s48, -1
	s_lshl_b64 s[46:47], s[46:47], s39
	global_store_short v[48:49], v43, off
	v_lshl_add_u64 v[48:49], s[46:47], 1, v[12:13]
	s_add_u32 s46, s41, 0xffffffe6
	s_addc_u32 s47, s48, -1
	s_lshl_b64 s[46:47], s[46:47], s39
	global_store_short v[48:49], v42, off
	v_lshl_add_u64 v[48:49], s[46:47], 1, v[12:13]
	s_add_u32 s46, s41, 0xffffffe7
	s_addc_u32 s47, s48, -1
	s_lshl_b64 s[46:47], s[46:47], s39
	global_store_short v[48:49], v47, off
	v_lshl_add_u64 v[48:49], s[46:47], 1, v[12:13]
	global_store_short v[48:49], v28, off
	s_branch .LBB0_815

.LBB0_826:
	s_and_b64 vcc, exec, s[0:1]
	s_cbranch_vccnz .LBB0_828
.LBB0_828:
	s_mov_b64 s[0:1], 0
